# priority raised before handoff barriers plus LDS-DMA scalar preamble hoisted out of the softmax-0 slot
# speedup vs baseline: 1.0031x; 1.0015x over previous
.LBB0_1289:
	s_cmp_ge_i32 s35, s89
	s_waitcnt vmcnt(0) lgkmcnt(0)
	s_cselect_b64 vcc, -1, 0
	s_or_b64 s[68:69], vcc, s[68:69]
	s_andn2_b64 s[100:101], s[70:71], s[68:69]
	s_bitcmp1_b32 s34, 0
	s_cselect_b32 s99, 0x6800, 0
	s_cselect_b32 s98, 0x4800, 0
	v_add_u32_e32 v72, s99, v230
	v_add_u32_e32 v73, s99, v231
	v_add_u32_e32 v237, s98, v234
	v_add_u32_e32 v217, 0xd000, v237
	s_and_b64 vcc, exec, s[100:101]
	s_waitcnt vmcnt(0) lgkmcnt(0)
	s_setprio 1
	s_barrier
	s_cbranch_vccz .Lpp_slow
	v_mfma_f32_32x32x16_bf16 v[48:63], v[180:183], v[64:67], v[48:63]
	ds_read_b128 v[168:171], v72
	ds_read_b128 v[160:163], v72 offset:32
	v_mfma_f32_32x32x16_bf16 v[32:47], v[184:187], v[64:67], v[32:47]
	ds_read_b128 v[164:167], v72 offset:64
	ds_read_b128 v[152:155], v72 offset:96
	s_add_i32 s15, s15, 64
	s_mov_b32 s35, s34
	v_mfma_f32_32x32x16_bf16 v[16:31], v[192:195], v[64:67], v[16:31]
	ds_read_b128 v[156:159], v72 offset:128
	ds_read_b128 v[128:131], v72 offset:160
	s_add_i32 s34, s34, 1
	s_cmp_ge_u32 s34, s87
	v_mfma_f32_32x32x16_bf16 v[0:15], v[196:199], v[64:67], v[0:15]
	ds_read_b128 v[132:135], v72 offset:192
	ds_read_b128 v[136:139], v72 offset:224
	s_cselect_b64 s[68:69], -1, 0
	s_mov_b64 s[70:71], -1
	v_mfma_f32_32x32x16_bf16 v[48:63], v[176:179], v[68:71], v[48:63]
	ds_read_b128 v[140:143], v73 offset:17408
	ds_read_b128 v[144:147], v73 offset:17440
	s_mov_b32 vcc_lo, s99
	s_and_b32 s99, s34, 1
	s_mul_i32 s98, s99, 0x4800
	s_addk_i32 s98, 0x6800
	v_mfma_f32_32x32x16_bf16 v[32:47], v[200:203], v[68:71], v[32:47]
	ds_read_b128 v[148:151], v73 offset:17472
	ds_read_b128 v[208:211], v73 offset:17504
	s_mulk_i32 s99, 0x6800
	s_add_i32 s99, s99, s44
	s_add_i32 s98, s98, s44
	v_mfma_f32_32x32x16_bf16 v[16:31], v[204:207], v[68:71], v[16:31]
	s_lshl_b32 s94, s34, 18
	s_lshl_b32 s90, s34, 13
	s_lshl_b32 s91, s34, 7
	s_lshl_b32 s92, s34, s95
	v_mfma_f32_32x32x16_bf16 v[0:15], v[188:191], v[68:71], v[0:15]
	s_branch .Lfh
